# MLA loop: one static priority raise for waves 4-7 ahead of the loop, per-iteration priority flips removed
# speedup vs baseline: 1.0017x; 1.0017x over previous
; #define LAS __attribute__((address_space(3)))
; __device__ __forceinline__ float xhalf_max(float v) { float a = v, b = v; xhalf_swap(a, b); return fmaxf(a, b); }
; __device__ __forceinline__ s16x4 vtr(LAS const unsigned char* p) { return __builtin_bit_cast(s16x4, __builtin_amdgcn_ds_read_tr16_b64_v4i16((LAS s16x4*)p)); }
; __device__ __forceinline__ void softmax_pv_vf(WaveAttn& st, f32x16 s, const bf16x8 (&vf)[4]) {
;     ...
; #pragma unroll
;     for (int r = 1; r < 16; ++r) mx = fmaxf(mx, s[r]);
;     mx = xhalf_max(mx);
;     if (__builtin_amdgcn_ballot_w64(mx > st.m + 8.0f) != 0ull) {
;         const float mn = fmaxf(st.m, mx);
;         const float alpha = __builtin_amdgcn_exp2f(st.m - mn);
;         st.m = mn; st.l *= alpha;
; #pragma unroll
;         for (int r = 0; r < 16; ++r) { st.o0[r] *= alpha; st.o1[r] *= alpha; }
;     }
; __device__ __forceinline__ void mla_phase2(const bf16_t* QKV, bf16_t* O, LAS unsigned char* lds, int nseq, int wv) {
;     ...
;         for (int kt = 0; kt < SEQ / 128; ++kt) {
;             if (kt + 1 < SEQ / 128) MLA_LOAD(kt + 1, (kt + 1) & 1);
;             LAS const unsigned char* kb = lds + (kt & 1) * MLA_STAGE; LAS const unsigned char* vbuf = kb + 128 * MLA_KP;
; #pragma unroll
;             for (int sub = 0; sub < 4; ++sub) {
;                 f32x16 sa, sb;
; #pragma unroll
;                 for (int r = 0; r < 16; ++r) { sa[r] = 0.f; sb[r] = 0.f; }
;                 LAS const unsigned char* kp = kb + (sub * 32 + r32) * MLA_KP + hi * 16;
;                 __builtin_amdgcn_s_setprio(1);
; #pragma unroll
;                 for (int ds = 0; ds < 6; ++ds) { const bf16x8 kf = *(LAS const bf16x8*)(kp + ds * 32);
;                     sa = __builtin_amdgcn_mfma_f32_32x32x16_bf16(kf, qa[ds], sa, 0, 0, 0); sb = __builtin_amdgcn_mfma_f32_32x32x16_bf16(kf, qb2[ds], sb, 0, 0, 0); }
;                 __builtin_amdgcn_s_setprio(0);
;                 LAS const unsigned char* vb_ = vbuf + sub * 4096 + voff;
;                 bf16x8 vf[4];
; #pragma unroll
;                 for (int i = 0; i < 4; ++i) { const int off = (i >> 1) * 2048 + (i & 1) * 1024; const s16x4 lo_ = vtr(vb_ + off), hi_ = vtr(vb_ + off + 512);
;                     vf[i] = (bf16x8){lo_[0], lo_[1], lo_[2], lo_[3], hi_[0], hi_[1], hi_[2], hi_[3]}; }
.LBB0_441:
	s_or_b64 exec, exec, s[68:69]
	v_add_u32_e32 v67, 0x6800, v66
	v_add_u32_e32 v66, 0x8800, v66
	v_readfirstlane_b32 s1, v67
	v_lshl_add_u64 v[68:69], v[196:197], 0, s[66:67]
	s_mov_b32 m0, s1
	v_readfirstlane_b32 s1, v66
	global_load_lds_dwordx4 v[68:69], off
	v_lshl_add_u64 v[68:69], v[192:193], 0, s[66:67]
	s_mov_b32 m0, s1
	s_nop 0
	global_load_lds_dwordx4 v[68:69], off
	v_readlane_b32 s85, v255, 1
	s_nop 3
	s_cmp_ge_u32 s85, 0x100
	s_cbranch_scc0 .Lmla_prio
	s_setprio 1
.Lmla_prio:
.LBB0_442:
	s_bitcmp1_b32 s0, 0
	s_cselect_b32 s0, 0xa800, 0
	s_add_i32 s0, s0, 0
	v_add_u32_e32 v66, s0, v210
	v_add3_u32 v67, s0, v208, v206
	v_add_u32_e32 v214, v67, v207
	v_add_u32_e32 v215, v66, v211
	ds_read_b128 v[66:69], v215
	ds_read_b128 v[146:149], v215 offset:32
	ds_read_b128 v[150:153], v215 offset:64
	ds_read_b128 v[218:221], v215 offset:96
	ds_read_b128 v[232:235], v215 offset:128
	ds_read_b128 v[236:239], v215 offset:160
	s_waitcnt lgkmcnt(0)
	v_mfma_f32_32x32x16_bf16 v[82:97], v[66:69], v[98:101], 0
	v_mfma_f32_32x32x16_bf16 v[82:97], v[146:149], v[102:105], v[82:97]
	v_mfma_f32_32x32x16_bf16 v[66:81], v[66:69], v[106:109], 0
	v_mfma_f32_32x32x16_bf16 v[82:97], v[150:153], v[114:117], v[82:97]
	v_mfma_f32_32x32x16_bf16 v[66:81], v[146:149], v[110:113], v[66:81]
	v_mfma_f32_32x32x16_bf16 v[82:97], v[218:221], v[118:121], v[82:97]
	v_mfma_f32_32x32x16_bf16 v[66:81], v[150:153], v[122:125], v[66:81]
	ds_read_b64_tr_b16 v[158:159], v214 offset:26624
	ds_read_b64_tr_b16 v[160:161], v214 offset:27136
	ds_read_b64_tr_b16 v[150:151], v214 offset:27648
	ds_read_b64_tr_b16 v[152:153], v214 offset:28160
	ds_read_b64_tr_b16 v[154:155], v214 offset:28672
	ds_read_b64_tr_b16 v[156:157], v214 offset:29184
	ds_read_b64_tr_b16 v[146:147], v214 offset:29696
	ds_read_b64_tr_b16 v[148:149], v214 offset:30208
	v_mfma_f32_32x32x16_bf16 v[82:97], v[232:235], v[130:133], v[82:97]
	v_mfma_f32_32x32x16_bf16 v[66:81], v[218:221], v[126:129], v[66:81]
	v_mfma_f32_32x32x16_bf16 v[82:97], v[236:239], v[134:137], v[82:97]
	v_mfma_f32_32x32x16_bf16 v[66:81], v[232:235], v[138:141], v[66:81]
	s_nop 10
	v_max_f32_e32 v222, v83, v83
	v_max_f32_e32 v223, v82, v82
	v_max_f32_e32 v222, v223, v222
	v_max3_f32 v218, v222, v84, v85
	v_max3_f32 v218, v218, v86, v87
	v_max3_f32 v218, v218, v88, v89
	v_max3_f32 v218, v218, v90, v91
	v_max3_f32 v218, v218, v92, v93
	v_mfma_f32_32x32x16_bf16 v[66:81], v[236:239], v[142:145], v[66:81]
	v_max3_f32 v218, v218, v94, v95
	v_max3_f32 v218, v218, v96, v97
	v_mov_b32_e32 v219, v218
	s_nop 1
	v_permlane32_swap_b32 v218, v219
	s_nop 1
	s_nop 0
	v_max_f32_e32 v218, v218, v219
	v_add_f32_e32 v219, 0x41000000, v213
	v_cmp_gt_f32_e32 vcc, v218, v219
	s_cbranch_vccz .LBB0_444
	v_max_f32_e32 v219, v213, v218
	v_sub_f32_e32 v213, v213, v219
	v_exp_f32_e32 v218, v213
	v_mov_b32_e32 v213, v219
	v_mul_f32_e32 v217, v217, v218
	v_pk_mul_f32 v[64:65], v[64:65], v[218:219] op_sel_hi:[1,0]
	v_pk_mul_f32 v[62:63], v[62:63], v[218:219] op_sel_hi:[1,0]
	v_pk_mul_f32 v[60:61], v[60:61], v[218:219] op_sel_hi:[1,0]
	v_pk_mul_f32 v[58:59], v[58:59], v[218:219] op_sel_hi:[1,0]
	v_pk_mul_f32 v[56:57], v[56:57], v[218:219] op_sel_hi:[1,0]
	v_pk_mul_f32 v[54:55], v[54:55], v[218:219] op_sel_hi:[1,0]
	v_pk_mul_f32 v[52:53], v[52:53], v[218:219] op_sel_hi:[1,0]
	v_pk_mul_f32 v[50:51], v[50:51], v[218:219] op_sel_hi:[1,0]
	v_pk_mul_f32 v[48:49], v[48:49], v[218:219] op_sel_hi:[1,0]
	v_pk_mul_f32 v[46:47], v[46:47], v[218:219] op_sel_hi:[1,0]
	v_pk_mul_f32 v[44:45], v[44:45], v[218:219] op_sel_hi:[1,0]
	v_pk_mul_f32 v[42:43], v[42:43], v[218:219] op_sel_hi:[1,0]
	v_pk_mul_f32 v[40:41], v[40:41], v[218:219] op_sel_hi:[1,0]
	v_pk_mul_f32 v[38:39], v[38:39], v[218:219] op_sel_hi:[1,0]
	v_pk_mul_f32 v[36:37], v[36:37], v[218:219] op_sel_hi:[1,0]
	v_pk_mul_f32 v[34:35], v[34:35], v[218:219] op_sel_hi:[1,0]

; #define LAS __attribute__((address_space(3)))
; __device__ __forceinline__ unsigned cvtpk(float lo, float hi) { f32x2 v = {lo, hi}; bf16x2_t b = __builtin_convertvector(v, bf16x2_t); return __builtin_bit_cast(unsigned, b); }
; __device__ __forceinline__ s16x4 vtr(LAS const unsigned char* p) { return __builtin_bit_cast(s16x4, __builtin_amdgcn_ds_read_tr16_b64_v4i16((LAS s16x4*)p)); }
; __device__ __forceinline__ void softmax_pv_vf(WaveAttn& st, f32x16 s, const bf16x8 (&vf)[4]) {
;     ...
;     const float mn = st.m;
;     float ps = 0.f;
; #pragma unroll
;     for (int r = 0; r < 16; ++r) { s[r] = __builtin_amdgcn_exp2f(s[r] - mn); ps += s[r]; }
;     st.l += ps;
;     u32x4 p0, p1;
;     p0.x = cvtpk(s[0], s[1]); p0.y = cvtpk(s[2], s[3]); p0.z = cvtpk(s[4], s[5]); p0.w = cvtpk(s[6], s[7]);
;     p1.x = cvtpk(s[8], s[9]); p1.y = cvtpk(s[10], s[11]); p1.z = cvtpk(s[12], s[13]); p1.w = cvtpk(s[14], s[15]);
;     const bf16x8 pb0 = __builtin_bit_cast(bf16x8, p0), pb1 = __builtin_bit_cast(bf16x8, p1);
;     st.o0 = __builtin_amdgcn_mfma_f32_32x32x16_bf16(vf[0], pb0, st.o0, 0, 0, 0);
;     st.o1 = __builtin_amdgcn_mfma_f32_32x32x16_bf16(vf[2], pb0, st.o1, 0, 0, 0);
;     st.o0 = __builtin_amdgcn_mfma_f32_32x32x16_bf16(vf[1], pb1, st.o0, 0, 0, 0);
;     st.o1 = __builtin_amdgcn_mfma_f32_32x32x16_bf16(vf[3], pb1, st.o1, 0, 0, 0);
; __device__ __forceinline__ void mla_phase2(const bf16_t* QKV, bf16_t* O, LAS unsigned char* lds, int nseq, int wv) {
;     ...
;                 LAS const unsigned char* kp = kb + (sub * 32 + r32) * MLA_KP + hi * 16;
;                 __builtin_amdgcn_s_setprio(1);
; #pragma unroll
;                 for (int ds = 0; ds < 6; ++ds) { const bf16x8 kf = *(LAS const bf16x8*)(kp + ds * 32);
;                     sa = __builtin_amdgcn_mfma_f32_32x32x16_bf16(kf, qa[ds], sa, 0, 0, 0); sb = __builtin_amdgcn_mfma_f32_32x32x16_bf16(kf, qb2[ds], sb, 0, 0, 0); }
;                 __builtin_amdgcn_s_setprio(0);
;                 LAS const unsigned char* vb_ = vbuf + sub * 4096 + voff;
;                 bf16x8 vf[4];
; #pragma unroll
;                 for (int i = 0; i < 4; ++i) { const int off = (i >> 1) * 2048 + (i & 1) * 1024; const s16x4 lo_ = vtr(vb_ + off), hi_ = vtr(vb_ + off + 512);
;                     vf[i] = (bf16x8){lo_[0], lo_[1], lo_[2], lo_[3], hi_[0], hi_[1], hi_[2], hi_[3]}; }
.LBB0_446:
	v_sub_f32_e32 v66, v66, v212
	v_exp_f32_e32 v218, v66
	v_sub_f32_e32 v66, v67, v212
	v_exp_f32_e32 v219, v66
	v_sub_f32_e32 v66, v68, v212
	v_exp_f32_e32 v220, v66
	v_sub_f32_e32 v66, v69, v212
	v_exp_f32_e32 v221, v66
	v_sub_f32_e32 v66, v70, v212
	v_exp_f32_e32 v222, v66
	v_sub_f32_e32 v66, v71, v212
	v_exp_f32_e32 v223, v66
	v_sub_f32_e32 v66, v72, v212
	v_exp_f32_e32 v231, v66
	v_sub_f32_e32 v66, v73, v212
	v_exp_f32_e32 v232, v66
	v_sub_f32_e32 v66, v74, v212
	v_exp_f32_e32 v233, v66
	v_sub_f32_e32 v66, v75, v212
	v_exp_f32_e32 v234, v66
	v_sub_f32_e32 v66, v76, v212
	v_exp_f32_e32 v235, v66
	v_sub_f32_e32 v66, v77, v212
	v_exp_f32_e32 v236, v66
	v_sub_f32_e32 v66, v78, v212
	v_exp_f32_e32 v237, v66
	v_sub_f32_e32 v66, v79, v212
	v_exp_f32_e32 v238, v66
	v_sub_f32_e32 v66, v80, v212
	v_exp_f32_e32 v239, v66
	v_sub_f32_e32 v66, v81, v212
	v_exp_f32_e32 v240, v66
	v_cvt_pk_bf16_f32 v66, v218, v219
	v_cvt_pk_bf16_f32 v67, v220, v221
	v_cvt_pk_bf16_f32 v68, v222, v223
	v_cvt_pk_bf16_f32 v69, v231, v232
	v_add_f32_e32 v82, v83, v82
	v_add_f32_e32 v82, v84, v82
	v_mfma_f32_32x32x16_bf16 v[18:33], v[158:161], v[66:69], v[18:33]
	v_add_f32_e32 v82, v85, v82
	v_add_f32_e32 v82, v86, v82
	v_add_f32_e32 v82, v87, v82
	v_add_f32_e32 v82, v88, v82
	v_add_f32_e32 v82, v89, v82
	v_add_f32_e32 v82, v90, v82
	v_cvt_pk_bf16_f32 v70, v233, v234
	v_mfma_f32_32x32x16_bf16 v[2:17], v[154:157], v[66:69], v[2:17]
	v_cvt_pk_bf16_f32 v71, v235, v236
	v_cvt_pk_bf16_f32 v72, v237, v238
	v_cvt_pk_bf16_f32 v73, v239, v240
	v_add_f32_e32 v82, v91, v82
	v_add_f32_e32 v82, v92, v82
	v_add_f32_e32 v82, v93, v82
	v_add_f32_e32 v82, v94, v82
	v_mfma_f32_32x32x16_bf16 v[18:33], v[150:153], v[70:73], v[18:33]
	v_add_f32_e32 v82, v95, v82
	v_add_f32_e32 v82, v96, v82
	v_add_f32_e32 v82, v97, v82
	v_add_f32_e32 v217, v217, v82
	v_mfma_f32_32x32x16_bf16 v[2:17], v[146:149], v[70:73], v[2:17]
	ds_read_b128 v[66:69], v215 offset:6656
	ds_read_b128 v[146:149], v215 offset:6688
	ds_read_b128 v[150:153], v215 offset:6720
	ds_read_b128 v[242:245], v215 offset:6752
	ds_read_b128 v[246:249], v215 offset:6784
	ds_read_b128 v[250:253], v215 offset:6816
	s_waitcnt lgkmcnt(5)
	v_mfma_f32_32x32x16_bf16 v[82:97], v[66:69], v[98:101], 0
	s_waitcnt lgkmcnt(4)
	v_mfma_f32_32x32x16_bf16 v[82:97], v[146:149], v[102:105], v[82:97]
	v_mfma_f32_32x32x16_bf16 v[66:81], v[66:69], v[106:109], 0
	s_waitcnt lgkmcnt(3)
	v_mfma_f32_32x32x16_bf16 v[82:97], v[150:153], v[114:117], v[82:97]
	v_mfma_f32_32x32x16_bf16 v[66:81], v[146:149], v[110:113], v[66:81]
	s_waitcnt lgkmcnt(2)
	v_mfma_f32_32x32x16_bf16 v[82:97], v[242:245], v[118:121], v[82:97]
	v_mfma_f32_32x32x16_bf16 v[66:81], v[150:153], v[122:125], v[66:81]
	ds_read_b64_tr_b16 v[158:159], v214 offset:30720
	ds_read_b64_tr_b16 v[160:161], v214 offset:31232
	ds_read_b64_tr_b16 v[150:151], v214 offset:31744
	ds_read_b64_tr_b16 v[152:153], v214 offset:32256
	ds_read_b64_tr_b16 v[154:155], v214 offset:32768
	ds_read_b64_tr_b16 v[156:157], v214 offset:33280
	ds_read_b64_tr_b16 v[146:147], v214 offset:33792
	ds_read_b64_tr_b16 v[148:149], v214 offset:34304
	s_waitcnt lgkmcnt(9)
	v_mfma_f32_32x32x16_bf16 v[82:97], v[246:249], v[130:133], v[82:97]
	v_mfma_f32_32x32x16_bf16 v[66:81], v[242:245], v[126:129], v[66:81]
	s_waitcnt lgkmcnt(8)
	v_mfma_f32_32x32x16_bf16 v[82:97], v[250:253], v[134:137], v[82:97]
	v_mfma_f32_32x32x16_bf16 v[66:81], v[246:249], v[138:141], v[66:81]
	s_nop 10
	v_max_f32_e32 v224, v82, v83
	v_max3_f32 v224, v224, v84, v85
	v_max3_f32 v224, v224, v86, v87
	v_max3_f32 v224, v224, v88, v89
	v_max3_f32 v224, v224, v90, v91
	v_max3_f32 v224, v224, v92, v93
	v_mfma_f32_32x32x16_bf16 v[66:81], v[250:253], v[142:145], v[66:81]
	v_max3_f32 v224, v224, v94, v95
	v_max3_f32 v224, v224, v96, v97
	v_mov_b32_e32 v225, v224
	s_nop 1
	v_permlane32_swap_b32 v224, v225
	s_nop 1
	s_nop 0
	v_max_f32_e32 v225, v225, v225
	v_max_f32_e32 v224, v224, v224
	v_max_f32_e32 v241, v224, v225
	v_add_f32_e32 v224, 0x41000000, v213
	v_cmp_gt_f32_e32 vcc, v241, v224
	s_cbranch_vccz .LBB0_448
	v_max_f32_e32 v225, v213, v241
	v_sub_f32_e32 v213, v213, v225
	v_exp_f32_e32 v224, v213
	v_mov_b32_e32 v213, v225
	v_mul_f32_e32 v217, v217, v224
	v_pk_mul_f32 v[64:65], v[64:65], v[224:225] op_sel_hi:[1,0]
	v_pk_mul_f32 v[62:63], v[62:63], v[224:225] op_sel_hi:[1,0]
	v_pk_mul_f32 v[60:61], v[60:61], v[224:225] op_sel_hi:[1,0]
	v_pk_mul_f32 v[58:59], v[58:59], v[224:225] op_sel_hi:[1,0]
	v_pk_mul_f32 v[56:57], v[56:57], v[224:225] op_sel_hi:[1,0]
	v_pk_mul_f32 v[54:55], v[54:55], v[224:225] op_sel_hi:[1,0]
	v_pk_mul_f32 v[52:53], v[52:53], v[224:225] op_sel_hi:[1,0]
	v_pk_mul_f32 v[50:51], v[50:51], v[224:225] op_sel_hi:[1,0]
	v_pk_mul_f32 v[48:49], v[48:49], v[224:225] op_sel_hi:[1,0]
	v_pk_mul_f32 v[46:47], v[46:47], v[224:225] op_sel_hi:[1,0]
	v_pk_mul_f32 v[44:45], v[44:45], v[224:225] op_sel_hi:[1,0]
	v_pk_mul_f32 v[42:43], v[42:43], v[224:225] op_sel_hi:[1,0]
	v_pk_mul_f32 v[40:41], v[40:41], v[224:225] op_sel_hi:[1,0]
	v_pk_mul_f32 v[38:39], v[38:39], v[224:225] op_sel_hi:[1,0]
	v_pk_mul_f32 v[36:37], v[36:37], v[224:225] op_sel_hi:[1,0]
	v_pk_mul_f32 v[34:35], v[34:35], v[224:225] op_sel_hi:[1,0]

; #define LAS __attribute__((address_space(3)))
; __device__ __forceinline__ unsigned cvtpk(float lo, float hi) { f32x2 v = {lo, hi}; bf16x2_t b = __builtin_convertvector(v, bf16x2_t); return __builtin_bit_cast(unsigned, b); }
; __device__ __forceinline__ s16x4 vtr(LAS const unsigned char* p) { return __builtin_bit_cast(s16x4, __builtin_amdgcn_ds_read_tr16_b64_v4i16((LAS s16x4*)p)); }
; __device__ __forceinline__ void softmax_pv_vf(WaveAttn& st, f32x16 s, const bf16x8 (&vf)[4]) {
;     ...
;     const float mn = st.m;
;     float ps = 0.f;
; #pragma unroll
;     for (int r = 0; r < 16; ++r) { s[r] = __builtin_amdgcn_exp2f(s[r] - mn); ps += s[r]; }
;     st.l += ps;
;     u32x4 p0, p1;
;     p0.x = cvtpk(s[0], s[1]); p0.y = cvtpk(s[2], s[3]); p0.z = cvtpk(s[4], s[5]); p0.w = cvtpk(s[6], s[7]);
;     p1.x = cvtpk(s[8], s[9]); p1.y = cvtpk(s[10], s[11]); p1.z = cvtpk(s[12], s[13]); p1.w = cvtpk(s[14], s[15]);
;     const bf16x8 pb0 = __builtin_bit_cast(bf16x8, p0), pb1 = __builtin_bit_cast(bf16x8, p1);
;     st.o0 = __builtin_amdgcn_mfma_f32_32x32x16_bf16(vf[0], pb0, st.o0, 0, 0, 0);
;     st.o1 = __builtin_amdgcn_mfma_f32_32x32x16_bf16(vf[2], pb0, st.o1, 0, 0, 0);
;     st.o0 = __builtin_amdgcn_mfma_f32_32x32x16_bf16(vf[1], pb1, st.o0, 0, 0, 0);
;     st.o1 = __builtin_amdgcn_mfma_f32_32x32x16_bf16(vf[3], pb1, st.o1, 0, 0, 0);
; __device__ __forceinline__ void mla_phase2(const bf16_t* QKV, bf16_t* O, LAS unsigned char* lds, int nseq, int wv) {
;     ...
;                 LAS const unsigned char* kp = kb + (sub * 32 + r32) * MLA_KP + hi * 16;
;                 __builtin_amdgcn_s_setprio(1);
; #pragma unroll
;                 for (int ds = 0; ds < 6; ++ds) { const bf16x8 kf = *(LAS const bf16x8*)(kp + ds * 32);
;                     sa = __builtin_amdgcn_mfma_f32_32x32x16_bf16(kf, qa[ds], sa, 0, 0, 0); sb = __builtin_amdgcn_mfma_f32_32x32x16_bf16(kf, qb2[ds], sb, 0, 0, 0); }
;                 __builtin_amdgcn_s_setprio(0);
;                 LAS const unsigned char* vb_ = vbuf + sub * 4096 + voff;
;                 bf16x8 vf[4];
; #pragma unroll
;                 for (int i = 0; i < 4; ++i) { const int off = (i >> 1) * 2048 + (i & 1) * 1024; const s16x4 lo_ = vtr(vb_ + off), hi_ = vtr(vb_ + off + 512);
;                     vf[i] = (bf16x8){lo_[0], lo_[1], lo_[2], lo_[3], hi_[0], hi_[1], hi_[2], hi_[3]}; }
.LBB0_450:
	v_sub_f32_e32 v66, v66, v212
	v_exp_f32_e32 v218, v66
	v_sub_f32_e32 v66, v67, v212
	v_exp_f32_e32 v219, v66
	v_sub_f32_e32 v66, v68, v212
	v_exp_f32_e32 v220, v66
	v_sub_f32_e32 v66, v69, v212
	v_exp_f32_e32 v221, v66
	v_sub_f32_e32 v66, v70, v212
	v_exp_f32_e32 v222, v66
	v_sub_f32_e32 v66, v71, v212
	v_exp_f32_e32 v223, v66
	v_sub_f32_e32 v66, v72, v212
	v_exp_f32_e32 v231, v66
	v_sub_f32_e32 v66, v73, v212
	v_exp_f32_e32 v232, v66
	v_sub_f32_e32 v66, v74, v212
	v_exp_f32_e32 v233, v66
	v_sub_f32_e32 v66, v75, v212
	v_exp_f32_e32 v234, v66
	v_sub_f32_e32 v66, v76, v212
	v_exp_f32_e32 v235, v66
	v_sub_f32_e32 v66, v77, v212
	v_exp_f32_e32 v236, v66
	v_sub_f32_e32 v66, v78, v212
	v_exp_f32_e32 v237, v66
	v_sub_f32_e32 v66, v79, v212
	v_exp_f32_e32 v238, v66
	v_sub_f32_e32 v66, v80, v212
	v_exp_f32_e32 v239, v66
	v_sub_f32_e32 v66, v81, v212
	v_exp_f32_e32 v240, v66
	v_cvt_pk_bf16_f32 v66, v218, v219
	v_cvt_pk_bf16_f32 v67, v220, v221
	v_cvt_pk_bf16_f32 v68, v222, v223
	v_cvt_pk_bf16_f32 v69, v231, v232
	v_add_f32_e32 v82, v83, v82
	v_add_f32_e32 v82, v84, v82
	v_mfma_f32_32x32x16_bf16 v[18:33], v[158:161], v[66:69], v[18:33]
	v_add_f32_e32 v82, v85, v82
	v_add_f32_e32 v82, v86, v82
	v_add_f32_e32 v82, v87, v82
	v_add_f32_e32 v82, v88, v82
	v_add_f32_e32 v82, v89, v82
	v_add_f32_e32 v82, v90, v82
	v_cvt_pk_bf16_f32 v70, v233, v234
	v_mfma_f32_32x32x16_bf16 v[2:17], v[154:157], v[66:69], v[2:17]
	v_cvt_pk_bf16_f32 v71, v235, v236
	v_cvt_pk_bf16_f32 v72, v237, v238
	v_cvt_pk_bf16_f32 v73, v239, v240
	v_add_f32_e32 v82, v91, v82
	v_add_f32_e32 v82, v92, v82
	v_add_f32_e32 v82, v93, v82
	v_add_f32_e32 v82, v94, v82
	v_mfma_f32_32x32x16_bf16 v[18:33], v[150:153], v[70:73], v[18:33]
	v_add_f32_e32 v82, v95, v82
	v_add_f32_e32 v82, v96, v82
	v_add_f32_e32 v82, v97, v82
	v_add_f32_e32 v217, v217, v82
	v_mfma_f32_32x32x16_bf16 v[2:17], v[146:149], v[70:73], v[2:17]
	ds_read_b128 v[66:69], v215 offset:13312
	ds_read_b128 v[146:149], v215 offset:13344
	ds_read_b128 v[150:153], v215 offset:13376
	ds_read_b128 v[242:245], v215 offset:13408
	ds_read_b128 v[246:249], v215 offset:13440
	ds_read_b128 v[250:253], v215 offset:13472
	s_waitcnt lgkmcnt(5)
	v_mfma_f32_32x32x16_bf16 v[82:97], v[66:69], v[98:101], 0
	s_waitcnt lgkmcnt(4)
	v_mfma_f32_32x32x16_bf16 v[82:97], v[146:149], v[102:105], v[82:97]
	v_mfma_f32_32x32x16_bf16 v[66:81], v[66:69], v[106:109], 0
	s_waitcnt lgkmcnt(3)
	v_mfma_f32_32x32x16_bf16 v[82:97], v[150:153], v[114:117], v[82:97]
	v_mfma_f32_32x32x16_bf16 v[66:81], v[146:149], v[110:113], v[66:81]
	s_waitcnt lgkmcnt(2)
	v_mfma_f32_32x32x16_bf16 v[82:97], v[242:245], v[118:121], v[82:97]
	v_mfma_f32_32x32x16_bf16 v[66:81], v[150:153], v[122:125], v[66:81]
	ds_read_b64_tr_b16 v[158:159], v214 offset:34816
	ds_read_b64_tr_b16 v[160:161], v214 offset:35328
	ds_read_b64_tr_b16 v[150:151], v214 offset:35840
	ds_read_b64_tr_b16 v[152:153], v214 offset:36352
	ds_read_b64_tr_b16 v[154:155], v214 offset:36864
	ds_read_b64_tr_b16 v[156:157], v214 offset:37376
	ds_read_b64_tr_b16 v[146:147], v214 offset:37888
	ds_read_b64_tr_b16 v[148:149], v214 offset:38400
	s_waitcnt lgkmcnt(9)
	v_mfma_f32_32x32x16_bf16 v[82:97], v[246:249], v[130:133], v[82:97]
	v_mfma_f32_32x32x16_bf16 v[66:81], v[242:245], v[126:129], v[66:81]
	s_waitcnt lgkmcnt(8)
	v_mfma_f32_32x32x16_bf16 v[82:97], v[250:253], v[134:137], v[82:97]
	v_mfma_f32_32x32x16_bf16 v[66:81], v[246:249], v[138:141], v[66:81]
	s_nop 10
	v_max_f32_e32 v224, v82, v83
	v_max3_f32 v224, v224, v84, v85
	v_max3_f32 v224, v224, v86, v87
	v_max3_f32 v224, v224, v88, v89
	v_max3_f32 v224, v224, v90, v91
	v_max3_f32 v224, v224, v92, v93
	v_mfma_f32_32x32x16_bf16 v[66:81], v[250:253], v[142:145], v[66:81]
	v_max3_f32 v224, v224, v94, v95
	v_max3_f32 v224, v224, v96, v97
	v_mov_b32_e32 v225, v224
	s_nop 1
	v_permlane32_swap_b32 v224, v225
	s_nop 1
	s_nop 0
	v_max_f32_e32 v225, v225, v225
	v_max_f32_e32 v224, v224, v224
	v_max_f32_e32 v241, v224, v225
	v_add_f32_e32 v224, 0x41000000, v213
	v_cmp_gt_f32_e32 vcc, v241, v224
	s_cbranch_vccz .LBB0_452
	v_max_f32_e32 v225, v213, v241
	v_sub_f32_e32 v213, v213, v225
	v_exp_f32_e32 v224, v213
	v_mov_b32_e32 v213, v225
	v_mul_f32_e32 v217, v217, v224
	v_pk_mul_f32 v[64:65], v[64:65], v[224:225] op_sel_hi:[1,0]
	v_pk_mul_f32 v[62:63], v[62:63], v[224:225] op_sel_hi:[1,0]
	v_pk_mul_f32 v[60:61], v[60:61], v[224:225] op_sel_hi:[1,0]
	v_pk_mul_f32 v[58:59], v[58:59], v[224:225] op_sel_hi:[1,0]
	v_pk_mul_f32 v[56:57], v[56:57], v[224:225] op_sel_hi:[1,0]
	v_pk_mul_f32 v[54:55], v[54:55], v[224:225] op_sel_hi:[1,0]
	v_pk_mul_f32 v[52:53], v[52:53], v[224:225] op_sel_hi:[1,0]
	v_pk_mul_f32 v[50:51], v[50:51], v[224:225] op_sel_hi:[1,0]
	v_pk_mul_f32 v[48:49], v[48:49], v[224:225] op_sel_hi:[1,0]
	v_pk_mul_f32 v[46:47], v[46:47], v[224:225] op_sel_hi:[1,0]
	v_pk_mul_f32 v[44:45], v[44:45], v[224:225] op_sel_hi:[1,0]
	v_pk_mul_f32 v[42:43], v[42:43], v[224:225] op_sel_hi:[1,0]
	v_pk_mul_f32 v[40:41], v[40:41], v[224:225] op_sel_hi:[1,0]
	v_pk_mul_f32 v[38:39], v[38:39], v[224:225] op_sel_hi:[1,0]
	v_pk_mul_f32 v[36:37], v[36:37], v[224:225] op_sel_hi:[1,0]
	v_pk_mul_f32 v[34:35], v[34:35], v[224:225] op_sel_hi:[1,0]

; #define LAS __attribute__((address_space(3)))
; __device__ __forceinline__ unsigned cvtpk(float lo, float hi) { f32x2 v = {lo, hi}; bf16x2_t b = __builtin_convertvector(v, bf16x2_t); return __builtin_bit_cast(unsigned, b); }
; __device__ __forceinline__ s16x4 vtr(LAS const unsigned char* p) { return __builtin_bit_cast(s16x4, __builtin_amdgcn_ds_read_tr16_b64_v4i16((LAS s16x4*)p)); }
; __device__ __forceinline__ void softmax_pv_vf(WaveAttn& st, f32x16 s, const bf16x8 (&vf)[4]) {
;     ...
;     const float mn = st.m;
;     float ps = 0.f;
; #pragma unroll
;     for (int r = 0; r < 16; ++r) { s[r] = __builtin_amdgcn_exp2f(s[r] - mn); ps += s[r]; }
;     st.l += ps;
;     u32x4 p0, p1;
;     p0.x = cvtpk(s[0], s[1]); p0.y = cvtpk(s[2], s[3]); p0.z = cvtpk(s[4], s[5]); p0.w = cvtpk(s[6], s[7]);
;     p1.x = cvtpk(s[8], s[9]); p1.y = cvtpk(s[10], s[11]); p1.z = cvtpk(s[12], s[13]); p1.w = cvtpk(s[14], s[15]);
;     const bf16x8 pb0 = __builtin_bit_cast(bf16x8, p0), pb1 = __builtin_bit_cast(bf16x8, p1);
;     st.o0 = __builtin_amdgcn_mfma_f32_32x32x16_bf16(vf[0], pb0, st.o0, 0, 0, 0);
;     st.o1 = __builtin_amdgcn_mfma_f32_32x32x16_bf16(vf[2], pb0, st.o1, 0, 0, 0);
;     st.o0 = __builtin_amdgcn_mfma_f32_32x32x16_bf16(vf[1], pb1, st.o0, 0, 0, 0);
;     st.o1 = __builtin_amdgcn_mfma_f32_32x32x16_bf16(vf[3], pb1, st.o1, 0, 0, 0);
; __device__ __forceinline__ void mla_phase2(const bf16_t* QKV, bf16_t* O, LAS unsigned char* lds, int nseq, int wv) {
;     ...
;                 LAS const unsigned char* kp = kb + (sub * 32 + r32) * MLA_KP + hi * 16;
;                 __builtin_amdgcn_s_setprio(1);
; #pragma unroll
;                 for (int ds = 0; ds < 6; ++ds) { const bf16x8 kf = *(LAS const bf16x8*)(kp + ds * 32);
;                     sa = __builtin_amdgcn_mfma_f32_32x32x16_bf16(kf, qa[ds], sa, 0, 0, 0); sb = __builtin_amdgcn_mfma_f32_32x32x16_bf16(kf, qb2[ds], sb, 0, 0, 0); }
;                 __builtin_amdgcn_s_setprio(0);
;                 LAS const unsigned char* vb_ = vbuf + sub * 4096 + voff;
;                 bf16x8 vf[4];
; #pragma unroll
;                 for (int i = 0; i < 4; ++i) { const int off = (i >> 1) * 2048 + (i & 1) * 1024; const s16x4 lo_ = vtr(vb_ + off), hi_ = vtr(vb_ + off + 512);
;                     vf[i] = (bf16x8){lo_[0], lo_[1], lo_[2], lo_[3], hi_[0], hi_[1], hi_[2], hi_[3]}; }
.LBB0_454:
	v_sub_f32_e32 v66, v66, v212
	v_exp_f32_e32 v218, v66
	v_sub_f32_e32 v66, v67, v212
	v_exp_f32_e32 v219, v66
	v_sub_f32_e32 v66, v68, v212
	v_exp_f32_e32 v220, v66
	v_sub_f32_e32 v66, v69, v212
	v_exp_f32_e32 v221, v66
	v_sub_f32_e32 v66, v70, v212
	v_exp_f32_e32 v222, v66
	v_sub_f32_e32 v66, v71, v212
	v_exp_f32_e32 v223, v66
	v_sub_f32_e32 v66, v72, v212
	v_exp_f32_e32 v231, v66
	v_sub_f32_e32 v66, v73, v212
	v_exp_f32_e32 v232, v66
	v_sub_f32_e32 v66, v74, v212
	v_exp_f32_e32 v233, v66
	v_sub_f32_e32 v66, v75, v212
	v_exp_f32_e32 v234, v66
	v_sub_f32_e32 v66, v76, v212
	v_exp_f32_e32 v235, v66
	v_sub_f32_e32 v66, v77, v212
	v_exp_f32_e32 v236, v66
	v_sub_f32_e32 v66, v78, v212
	v_exp_f32_e32 v237, v66
	v_sub_f32_e32 v66, v79, v212
	v_exp_f32_e32 v238, v66
	v_sub_f32_e32 v66, v80, v212
	v_exp_f32_e32 v239, v66
	v_sub_f32_e32 v66, v81, v212
	v_exp_f32_e32 v240, v66
	v_cvt_pk_bf16_f32 v66, v218, v219
	v_cvt_pk_bf16_f32 v67, v220, v221
	v_cvt_pk_bf16_f32 v68, v222, v223
	v_cvt_pk_bf16_f32 v69, v231, v232
	v_add_f32_e32 v82, v83, v82
	v_add_f32_e32 v82, v84, v82
	v_mfma_f32_32x32x16_bf16 v[18:33], v[158:161], v[66:69], v[18:33]
	v_add_f32_e32 v82, v85, v82
	v_add_f32_e32 v82, v86, v82
	v_add_f32_e32 v82, v87, v82
	v_add_f32_e32 v82, v88, v82
	v_add_f32_e32 v82, v89, v82
	v_add_f32_e32 v82, v90, v82
	v_cvt_pk_bf16_f32 v70, v233, v234
	v_mfma_f32_32x32x16_bf16 v[2:17], v[154:157], v[66:69], v[2:17]
	v_cvt_pk_bf16_f32 v71, v235, v236
	v_cvt_pk_bf16_f32 v72, v237, v238
	v_cvt_pk_bf16_f32 v73, v239, v240
	v_add_f32_e32 v82, v91, v82
	v_add_f32_e32 v82, v92, v82
	v_add_f32_e32 v82, v93, v82
	v_add_f32_e32 v82, v94, v82
	v_mfma_f32_32x32x16_bf16 v[18:33], v[150:153], v[70:73], v[18:33]
	v_add_f32_e32 v82, v95, v82
	v_add_f32_e32 v82, v96, v82
	v_add_f32_e32 v82, v97, v82
	v_add_f32_e32 v217, v217, v82
	v_mfma_f32_32x32x16_bf16 v[2:17], v[146:149], v[70:73], v[2:17]
	ds_read_b128 v[66:69], v215 offset:19968
	ds_read_b128 v[146:149], v215 offset:20000
	ds_read_b128 v[150:153], v215 offset:20032
	ds_read_b128 v[242:245], v215 offset:20064
	ds_read_b128 v[246:249], v215 offset:20096
	ds_read_b128 v[250:253], v215 offset:20128
	s_waitcnt lgkmcnt(5)
	v_mfma_f32_32x32x16_bf16 v[82:97], v[66:69], v[98:101], 0
	s_waitcnt lgkmcnt(4)
	v_mfma_f32_32x32x16_bf16 v[82:97], v[146:149], v[102:105], v[82:97]
	v_mfma_f32_32x32x16_bf16 v[66:81], v[66:69], v[106:109], 0
	s_waitcnt lgkmcnt(3)
	v_mfma_f32_32x32x16_bf16 v[82:97], v[150:153], v[114:117], v[82:97]
	v_mfma_f32_32x32x16_bf16 v[66:81], v[146:149], v[110:113], v[66:81]
	s_waitcnt lgkmcnt(2)
	v_mfma_f32_32x32x16_bf16 v[82:97], v[242:245], v[118:121], v[82:97]
	v_mfma_f32_32x32x16_bf16 v[66:81], v[150:153], v[122:125], v[66:81]
	ds_read_b64_tr_b16 v[158:159], v214 offset:38912
	ds_read_b64_tr_b16 v[160:161], v214 offset:39424
	ds_read_b64_tr_b16 v[150:151], v214 offset:39936
	ds_read_b64_tr_b16 v[152:153], v214 offset:40448
	ds_read_b64_tr_b16 v[154:155], v214 offset:40960
	ds_read_b64_tr_b16 v[156:157], v214 offset:41472
	ds_read_b64_tr_b16 v[146:147], v214 offset:41984
	ds_read_b64_tr_b16 v[148:149], v214 offset:42496
	s_waitcnt lgkmcnt(9)
	v_mfma_f32_32x32x16_bf16 v[82:97], v[246:249], v[130:133], v[82:97]
	v_mfma_f32_32x32x16_bf16 v[66:81], v[242:245], v[126:129], v[66:81]
	s_waitcnt lgkmcnt(8)
	v_mfma_f32_32x32x16_bf16 v[82:97], v[250:253], v[134:137], v[82:97]
	v_mfma_f32_32x32x16_bf16 v[66:81], v[246:249], v[138:141], v[66:81]
	s_nop 10
	v_max_f32_e32 v214, v82, v83
	v_max3_f32 v214, v214, v84, v85
	v_max3_f32 v214, v214, v86, v87
	v_max3_f32 v214, v214, v88, v89
	v_max3_f32 v214, v214, v90, v91
	v_max3_f32 v214, v214, v92, v93
	v_mfma_f32_32x32x16_bf16 v[66:81], v[250:253], v[142:145], v[66:81]
	v_max3_f32 v214, v214, v94, v95
	v_max3_f32 v214, v214, v96, v97
	v_mov_b32_e32 v215, v214
	s_nop 1
	v_permlane32_swap_b32 v214, v215
	s_nop 1
	s_nop 0
	v_max_f32_e32 v214, v214, v215
	v_add_f32_e32 v215, 0x41000000, v213
	v_cmp_gt_f32_e32 vcc, v214, v215
	s_cbranch_vccz .LBB0_456
	v_max_f32_e32 v215, v213, v214
	v_sub_f32_e32 v213, v213, v215
	v_exp_f32_e32 v214, v213
	v_mov_b32_e32 v213, v215
	v_mul_f32_e32 v217, v217, v214
	v_pk_mul_f32 v[64:65], v[64:65], v[214:215] op_sel_hi:[1,0]
	v_pk_mul_f32 v[62:63], v[62:63], v[214:215] op_sel_hi:[1,0]
	v_pk_mul_f32 v[60:61], v[60:61], v[214:215] op_sel_hi:[1,0]
	v_pk_mul_f32 v[58:59], v[58:59], v[214:215] op_sel_hi:[1,0]
	v_pk_mul_f32 v[56:57], v[56:57], v[214:215] op_sel_hi:[1,0]
	v_pk_mul_f32 v[54:55], v[54:55], v[214:215] op_sel_hi:[1,0]
	v_pk_mul_f32 v[52:53], v[52:53], v[214:215] op_sel_hi:[1,0]
	v_pk_mul_f32 v[50:51], v[50:51], v[214:215] op_sel_hi:[1,0]
	v_pk_mul_f32 v[48:49], v[48:49], v[214:215] op_sel_hi:[1,0]
	v_pk_mul_f32 v[46:47], v[46:47], v[214:215] op_sel_hi:[1,0]
	v_pk_mul_f32 v[44:45], v[44:45], v[214:215] op_sel_hi:[1,0]
	v_pk_mul_f32 v[42:43], v[42:43], v[214:215] op_sel_hi:[1,0]
	v_pk_mul_f32 v[40:41], v[40:41], v[214:215] op_sel_hi:[1,0]
	v_pk_mul_f32 v[38:39], v[38:39], v[214:215] op_sel_hi:[1,0]
	v_pk_mul_f32 v[36:37], v[36:37], v[214:215] op_sel_hi:[1,0]
	v_pk_mul_f32 v[34:35], v[34:35], v[214:215] op_sel_hi:[1,0]

; #define LAS __attribute__((address_space(3)))
; __device__ __forceinline__ int ltid(int wv) { unsigned z = 0u; asm volatile("" : "+v"(z)); return wv * 64 + (int)__builtin_amdgcn_mbcnt_hi(~0u, __builtin_amdgcn_mbcnt_lo(~0u, z)); }
; __device__ __forceinline__ void small_attn_phase(ArgP ap, int layer, const bf16_t* Z, bf16_t* O, bf16_t* OD, float* LSE, LAS unsigned char* lds, int tg, int wv) {
;     const int tid = ltid(wv), lane = tid & 63, wave = tid >> 6;
;     __syncthreads();
;     const float* tgl = (const float*)(ap->ws + WS_TAB);
;     for (int i = tid; i < 4 * 320; i += 512) { const int h_ = i / 320, off = i % 320 - 160; ((LAS float*)(lds + LDS_TSWA))[i] = (off >= -128 && off <= 128) ? tgl[h_ * 257 + off + 128] : NEGBIG; }
.LBB0_466:
	s_setprio 0
	v_mov_b32_e32 v0, v1
	v_readlane_b32 s0, v255, 1
	v_mbcnt_lo_u32_b32 v0, -1, v0
	v_mbcnt_hi_u32_b32 v0, -1, v0
	v_add_u32_e32 v2, s0, v0
	s_add_u32 s2, s18, 0x100000
	s_movk_i32 s0, 0x500
	s_addc_u32 s3, s19, 0
	v_cmp_gt_i32_e32 vcc, s0, v2
	s_waitcnt vmcnt(0) lgkmcnt(0)
	s_barrier
	s_and_saveexec_b64 s[4:5], vcc
	s_movk_i32 s10, 0x81
	s_movk_i32 s11, 0x101
	s_cbranch_execz .LBB0_471
	s_add_i32 s0, 0, 0x16000
	v_lshl_add_u32 v3, v2, 2, s0
	s_mov_b64 s[6:7], 0
	v_mov_b32_e32 v4, v2
	s_branch .LBB0_469
